# NSA far-tile loop: register prefetch of next tile (SGPR-addressed) issued after the tile scan
# speedup vs baseline: 1.0115x; 1.0064x over previous
;   DI int next(int t) const { for (int j = t + 1; j < 128; ++j) if (inu(j) && !farj(j)) return j; return -1; }
;   DI int next(int t) const { for (int j = t + 1; j < 128; ++j) if (inu(j) && farj(j)) return j; return -1; }
; template <int DK, bool PV, bool PF, class Ctx>
; DI void attn_run(const bf16x8 (&qf)[DK / 16], f32x16 (&o)[4], float& m, float& l, const bf16* K1, int ldk1,
;                  const bf16* K2, int ldk2, const bf16* Vt, int ldv, int first, Ctx& ctx, char* smem) {
;     ...
;   auto sstore = [&]() {
;     stk(0, rk0); stk(1, rk1); stk(2, rk2); stk(3, rk3);
;     if (NKC > 4) { stk(4, rk4); stk(5, rk5); }
; #pragma unroll
;     for (int i = 0; i < 4; ++i) {
;       int c = tid + 256 * i;
;       int d = c >> 3, cc = c & 7;
;       uint2* dst = (uint2*)(Vs + d * 68 + cc * 8);
;       dst[0] = make_uint2(rv[i].x, rv[i].y);
;       dst[1] = make_uint2(rv[i].z, rv[i].w);
;     }
;     if (tid < 64) ((float*)(smem + AT_AUX))[tid] = raux;
;   };
;   if (PF) gload(tcur * 64);
;   while (tcur >= 0) {
;     __syncthreads();
;     if (!PF) gload(tcur * 64);
;     sstore();
;     __syncthreads();
;     int tnext = ctx.next(tcur);
;     if (PF && tnext >= 0) gload(tnext * 64);
.LBB0_760:
	s_cmp_lt_i32 s26, 0
	s_mov_b32 s6, 0
	s_cbranch_scc1 .LBB0_776
	v_add_u32_e32 v7, s6, v189
	v_ashrrev_i32_e32 v0, 31, v7
	v_lshrrev_b32_e32 v0, 28, v0
	v_add_u32_e32 v0, v7, v0
	v_lshrrev_b32_e32 v2, 4, v0
	v_and_b32_e32 v0, 0xffffff0, v0
	v_sub_u32_e32 v0, v7, v0
	v_add_u32_e32 v4, 0x100, v7
	v_lshlrev_b32_e32 v9, 4, v0
	v_ashrrev_i32_e32 v0, 31, v4
	v_lshrrev_b32_e32 v0, 28, v0
	v_add_u32_e32 v0, v4, v0
	v_mul_lo_u32 v8, v2, s73
	v_lshrrev_b32_e32 v2, 4, v0
	v_and_b32_e32 v0, 0xffffff0, v0
	v_sub_u32_e32 v0, v4, v0
	v_add_u32_e32 v12, 0x200, v7
	v_lshlrev_b32_e32 v11, 4, v0
	v_ashrrev_i32_e32 v0, 31, v12
	v_lshrrev_b32_e32 v0, 28, v0
	v_add_u32_e32 v0, v12, v0
	v_mul_lo_u32 v10, v2, s73
	v_lshrrev_b32_e32 v2, 4, v0
	v_and_b32_e32 v0, 0xffffff0, v0
	v_sub_u32_e32 v0, v12, v0
	v_add_u32_e32 v80, 0x300, v7
	v_lshlrev_b32_e32 v82, 4, v0
	v_ashrrev_i32_e32 v0, 31, v80
	v_lshrrev_b32_e32 v0, 28, v0
	v_add_u32_e32 v0, v80, v0
	v_mul_lo_u32 v13, v2, s73
	v_lshrrev_b32_e32 v2, 4, v0
	v_and_b32_e32 v0, 0xffffff0, v0
	v_sub_u32_e32 v0, v80, v0
	v_lshlrev_b32_e32 v84, 4, v0
	v_lshlrev_b32_e32 v0, 4, v7
	v_mul_lo_u32 v83, v2, s73
	v_lshrrev_b32_e32 v2, 3, v7
	v_and_b32_e32 v0, 0x70, v0
	v_mad_u64_u32 v[2:3], s[6:7], v2, s68, v[0:1]
	v_lshrrev_b32_e32 v3, 3, v4
	v_mad_u64_u32 v[4:5], s[6:7], v3, s68, v[0:1]
	v_lshrrev_b32_e32 v3, 3, v12
	v_mad_u64_u32 v[14:15], s[6:7], v3, s68, v[0:1]
	v_lshrrev_b32_e32 v3, 3, v80
	v_mad_u64_u32 v[80:81], s[6:7], v3, s68, v[0:1]
	v_cmp_gt_i32_e64 s[10:11], 64, v7
	v_lshlrev_b32_e32 v7, 2, v7
	v_add_u32_e32 v8, v8, v9
	v_add_u32_e32 v9, v10, v11
	v_add_u32_e32 v10, v13, v82
	v_add_u32_e32 v11, v83, v84
	v_add_u32_e32 v12, 0x6400, v2
	v_add_u32_e32 v13, 0x6400, v4
	v_add_u32_e32 v14, 0x6400, v14
	v_add_u32_e32 v15, 0x6400, v80
	v_lshrrev_b32_e32 v252, 4, v189
	v_mul_u32_u24_e32 v252, 0x3500, v252
	v_and_b32_e32 v253, 15, v189
	v_lshl_add_u32 v252, v253, 4, v252
	v_lshrrev_b32_e32 v253, 3, v189
	v_lshlrev_b32_e32 v253, 14, v253
	v_and_b32_e32 v199, 7, v189
	v_lshl_or_b32 v253, v199, 4, v253
	s_branch .Lfar_first

; DI int otid() { int z; asm volatile("s_mov_b32 %0, 0" : "=s"(z)); return (int)threadIdx.x + z; }
;   DI float aux(int key) const { return (cuml[key] + cpre[key >> 7]) * LOG2E; }
;           DI float aux(int key) const { int n = key < 511 ? key : 510; return __int_as_float(pos[16 * n + 31]); }
;   DI float aux(int key) const { return __int_as_float(pos[key]); }
;   DI float aux(int key) const { return __int_as_float(pos[key]); }
; template <int DK, bool PV, bool PF, class Ctx>
; DI void attn_run(const bf16x8 (&qf)[DK / 16], f32x16 (&o)[4], float& m, float& l, const bf16* K1, int ldk1,
;                  const bf16* K2, int ldk2, const bf16* Vt, int ldv, int first, Ctx& ctx, char* smem) {
;     ...
;   auto gload = [&](int key0) {
;     rk0 = ldk(0, key0); rk1 = ldk(1, key0); rk2 = ldk(2, key0); rk3 = ldk(3, key0);
;     if (NKC > 4) { rk4 = ldk(4, key0); rk5 = ldk(5, key0); }
;     const int tl = otid();
; #pragma unroll
;     for (int i = 0; i < 4; ++i) {
;       int c = tl + 256 * i;
;       int d = c >> 3, cc = c & 7;
;       rv[i] = *(const uint4*)(Vt + (size_t)d * ldv + key0 + cc * 8);
;     }
;     raux = (tid < 64) ? ctx.aux(key0 + tid) : 0.f;
;   };
;   auto sstore = [&]() {
;     stk(0, rk0); stk(1, rk1); stk(2, rk2); stk(3, rk3);
;     if (NKC > 4) { stk(4, rk4); stk(5, rk5); }
; #pragma unroll
;     for (int i = 0; i < 4; ++i) {
;       int c = tid + 256 * i;
;       int d = c >> 3, cc = c & 7;
;       uint2* dst = (uint2*)(Vs + d * 68 + cc * 8);
;       dst[0] = make_uint2(rv[i].x, rv[i].y);
;       dst[1] = make_uint2(rv[i].z, rv[i].w);
;     }
;     if (tid < 64) ((float*)(smem + AT_AUX))[tid] = raux;
;   };
.Lfar_first:
	s_waitcnt lgkmcnt(0)
	s_barrier
	s_lshl_b32 s64, s26, 6
	s_mul_i32 s6, s64, s67
	s_add_u32 s6, s42, s6
	s_addc_u32 s7, s43, 0
	global_load_dwordx4 v[2:5], v252, s[6:7]
	s_add_u32 s6, s6, 0x35000
	s_addc_u32 s7, s7, 0
	global_load_dwordx4 v[80:83], v252, s[6:7]
	s_add_u32 s6, s6, 0x35000
	s_addc_u32 s7, s7, 0
	global_load_dwordx4 v[84:87], v252, s[6:7]
	s_add_u32 s6, s6, 0x35000
	s_addc_u32 s7, s7, 0
	global_load_dwordx4 v[88:91], v252, s[6:7]
	s_lshl_b32 s6, s64, 1
	s_add_u32 s6, s0, s6
	s_addc_u32 s7, s1, 0
	global_load_dwordx4 v[100:103], v253, s[6:7]
	s_add_u32 s6, s6, 0x80000
	s_addc_u32 s7, s7, 0
	global_load_dwordx4 v[104:107], v253, s[6:7]
	s_add_u32 s6, s6, 0x80000
	s_addc_u32 s7, s7, 0
	global_load_dwordx4 v[108:111], v253, s[6:7]
	s_add_u32 s6, s6, 0x80000
	s_addc_u32 s7, s7, 0
	s_waitcnt vmcnt(6)
	ds_write_b128 v8, v[2:5]
	global_load_dwordx4 v[2:5], v253, s[6:7]
	s_waitcnt vmcnt(6)
	ds_write_b128 v9, v[80:83]
	s_waitcnt vmcnt(5)
	ds_write_b128 v10, v[84:87]
	s_waitcnt vmcnt(4)
	ds_write_b128 v11, v[88:91]
	s_waitcnt vmcnt(3)
	ds_write2_b64 v12, v[100:101], v[102:103] offset1:1
	s_waitcnt vmcnt(2)
	ds_write2_b64 v13, v[104:105], v[106:107] offset1:1
	s_waitcnt vmcnt(1)
	ds_write2_b64 v14, v[108:109], v[110:111] offset1:1
	s_waitcnt vmcnt(0)
	ds_write2_b64 v15, v[2:3], v[4:5] offset1:1

; DI int otid() { int z; asm volatile("s_mov_b32 %0, 0" : "=s"(z)); return (int)threadIdx.x + z; }
;   DI float aux(int key) const { return (cuml[key] + cpre[key >> 7]) * LOG2E; }
;           DI float aux(int key) const { int n = key < 511 ? key : 510; return __int_as_float(pos[16 * n + 31]); }
;   DI int next(int t) const { for (int j = t + 1; j < 128; ++j) if (inu(j) && !farj(j)) return j; return -1; }
;   DI float aux(int key) const { return __int_as_float(pos[key]); }
;   DI int next(int t) const { for (int j = t + 1; j < 128; ++j) if (inu(j) && farj(j)) return j; return -1; }
;   DI float aux(int key) const { return __int_as_float(pos[key]); }
; template <int DK, bool PV, bool PF, class Ctx>
; DI void attn_run(const bf16x8 (&qf)[DK / 16], f32x16 (&o)[4], float& m, float& l, const bf16* K1, int ldk1,
;                  const bf16* K2, int ldk2, const bf16* Vt, int ldv, int first, Ctx& ctx, char* smem) {
;     ...
;   auto gload = [&](int key0) {
;     rk0 = ldk(0, key0); rk1 = ldk(1, key0); rk2 = ldk(2, key0); rk3 = ldk(3, key0);
;     if (NKC > 4) { rk4 = ldk(4, key0); rk5 = ldk(5, key0); }
;     const int tl = otid();
; #pragma unroll
;     for (int i = 0; i < 4; ++i) {
;       int c = tl + 256 * i;
;       int d = c >> 3, cc = c & 7;
;       rv[i] = *(const uint4*)(Vt + (size_t)d * ldv + key0 + cc * 8);
;     }
;     raux = (tid < 64) ? ctx.aux(key0 + tid) : 0.f;
;   };
;     ...
;     int tnext = ctx.next(tcur);
;     if (PF && tnext >= 0) gload(tnext * 64);
.LBB0_772:
	s_cmp_lt_i32 s6, 0
	s_cbranch_scc1 .Lfar_nopf
	s_lshl_b32 s64, s6, 6
	s_mul_i32 s12, s64, s67
	s_add_u32 s12, s42, s12
	s_addc_u32 s13, s43, 0
	global_load_dwordx4 v[196:199], v252, s[12:13]
	s_add_u32 s12, s12, 0x35000
	s_addc_u32 s13, s13, 0
	global_load_dwordx4 v[200:203], v252, s[12:13]
	s_add_u32 s12, s12, 0x35000
	s_addc_u32 s13, s13, 0
	global_load_dwordx4 v[204:207], v252, s[12:13]
	s_add_u32 s12, s12, 0x35000
	s_addc_u32 s13, s13, 0
	global_load_dwordx4 v[220:223], v252, s[12:13]
	s_lshl_b32 s12, s64, 1
	s_add_u32 s12, s0, s12
	s_addc_u32 s13, s1, 0
	global_load_dwordx4 v[240:243], v253, s[12:13]
	s_add_u32 s12, s12, 0x80000
	s_addc_u32 s13, s13, 0
	global_load_dwordx4 v[244:247], v253, s[12:13]
	s_add_u32 s12, s12, 0x80000
	s_addc_u32 s13, s13, 0
	global_load_dwordx4 v[248:251], v253, s[12:13]
	s_add_u32 s12, s12, 0x80000
	s_addc_u32 s13, s13, 0
	global_load_dwordx4 v[182:185], v253, s[12:13]
